# WF2 weight transposition moved from the norm2 phase to the 212 CUs idle in G4's last round
# baseline (speedup 1.0000x reference)
; __device__ __forceinline__ int opaque_tid() { int t = threadIdx.x; asm volatile("" : "+v"(t)); return t; }
; #define PH(b) if ((PHM >> (b)) & 1)
; #define PHASE_BEGIN unsigned char* ws = opaque_ptr(P.ws); const int z = opaque_zero(); (void)ws; (void)z;
; __global__ void __launch_bounds__(512, 2) mega_fwd(Params P) {
;     ...
;         for (int rep_ = 0; rep_ < ((PROBE_DUP & 32) ? 2 : 1); ++rep_) PH(1) { PHASE_BEGIN
;             const int tid = opaque_tid(), lane = tid & 63, wave = __builtin_amdgcn_readfirstlane(tid >> 6); const int gw = c * 8 + wave, NGW = (G + z) * 8;
;             const float* wf1 = PIN(I_WF1) + (size_t)l * D * 2 * DFF; const float* wf2 = PIN(I_WF2) + (size_t)l * DFF * D;
;             const int n1 = 32 * 44, n2 = 88 * 8;
;             { const int tot4 = (n1 + n2) * 4; const int s0 = (int)((unsigned)(gw * tot4) / (unsigned)NGW), s1 = (int)((unsigned)((gw + 1) * tot4) / (unsigned)NGW);
;             for (int ss = s0; ss < s1; ++ss) {
;                 const int it = ss >> 2, sub = ss & 3;
;                 if (it < n1) transpose_item<1>(wf1, D, 2 * DFF, WF1, it, sub, lane);
;                 else transpose_item<0>(wf2, DFF, D, WF2, it - n1, sub, lane);
;             } }
.LBB0_1573:
	v_writelane_b32 v254, s24, 57
	s_nop 1
	v_writelane_b32 v254, s25, 58
	s_or_b64 exec, exec, s[0:1]
	s_mov_b32 s100, s64
	s_mov_b32 s101, s51
	s_movk_i32 s4, 0x1600
	v_writelane_b32 v255, s4, 50
	s_nop 1
	s_mov_b32 s4, 0
	v_writelane_b32 v255, s4, 51
	s_nop 1
.Lw2_entry:
	v_readlane_b32 s0, v254, 28
	v_readlane_b32 s1, v254, 29
	v_mov_b32_e32 v3, v1
	v_mov_b32_e32 v0, s0
	v_mov_b32_e32 v2, s1
	s_nop 0
	v_readfirstlane_b32 s0, v3
	s_add_i32 s1, s0, s100
	s_lshl_b32 s1, s1, 3
	v_cvt_f32_u32_e32 v3, s1
	v_readfirstlane_b32 s16, v0
	v_mov_b32_e32 v0, v208
	v_rcp_iflag_f32_e32 v3, v3
	v_readfirstlane_b32 s4, v0
	s_sub_i32 s5, 0, s1
	s_lshr_b32 s4, s4, 6
	v_mul_f32_e32 v3, 0x4f7ffffe, v3
	v_cvt_u32_f32_e32 v3, v3
	s_add_i32 s4, s4, s101
	v_readlane_b32 s15, v255, 50
	s_nop 1
	s_mul_i32 s4, s4, s15
	v_readfirstlane_b32 s19, v2
	v_readfirstlane_b32 s14, v3
	s_mul_i32 s5, s5, s14
	s_mul_hi_u32 s5, s14, s5
	s_add_i32 s14, s14, s5
	s_mul_hi_u32 s5, s4, s14
	s_mul_i32 s15, s5, s1
	s_sub_i32 s15, s4, s15
	s_add_i32 s17, s5, 1
	s_sub_i32 s18, s15, s1
	s_cmp_ge_u32 s15, s1
	s_cselect_b32 s5, s17, s5
	s_cselect_b32 s15, s18, s15
	s_add_i32 s17, s5, 1
	s_cmp_ge_u32 s15, s1
	s_cselect_b32 s17, s17, s5
	v_readlane_b32 s5, v255, 50
	s_nop 1
	s_add_i32 s4, s4, s5
	s_mul_hi_u32 s5, s4, s14
	s_mul_i32 s14, s5, s1
	s_sub_i32 s4, s4, s14
	s_add_i32 s14, s5, 1
	s_sub_i32 s15, s4, s1
	s_cmp_ge_u32 s4, s1
	s_cselect_b32 s5, s14, s5
	s_cselect_b32 s4, s15, s4
	s_add_i32 s14, s5, 1
	s_cmp_ge_u32 s4, s1
	s_cselect_b32 s18, s14, s5
	v_readlane_b32 s5, v255, 51
	s_nop 1
	s_add_i32 s17, s17, s5
	s_add_i32 s18, s18, s5
	s_cmp_lt_i32 s17, s18
	s_cbranch_scc0 .LBB0_1584
	s_ashr_i32 s1, s0, 31
	s_lshl_b64 s[0:1], s[0:1], 3
	v_readlane_b32 s4, v254, 30
	v_readlane_b32 s5, v254, 31
	s_add_u32 s0, s4, s0
	s_addc_u32 s1, s5, s1
	s_load_dwordx4 s[28:31], s[0:1], 0xd8
	v_readlane_b32 s0, v254, 53
	s_mov_b32 s4, s0
	s_mul_i32 s0, s0, 0x5800000
	v_readlane_b32 s1, v254, 54
	s_waitcnt lgkmcnt(0)
	s_add_u32 s0, s28, s0
	s_mul_i32 s4, s4, 0x2c00000
	s_addc_u32 s1, s29, 0
	s_add_u32 s4, s30, s4
	v_lshlrev_b32_e32 v0, 2, v0
	s_addc_u32 s5, s31, 0
	v_and_b32_e32 v6, 0xfc, v0
	s_add_u32 s24, s16, 0x2c00000
	s_addc_u32 s25, s19, 0
	v_and_b32_e32 v7, 0x7c, v0
	v_or_b32_e32 v8, 0x80, v6
	s_branch .LBB0_1577

; __device__ __forceinline__ int opaque_tid() { int t = threadIdx.x; asm volatile("" : "+v"(t)); return t; }
; #define PH(b) if ((PHM >> (b)) & 1)
; #define PHASE_BEGIN unsigned char* ws = opaque_ptr(P.ws); const int z = opaque_zero(); (void)ws; (void)z;
; #define GSYNC() xcd_barrier(xbar)
; __global__ void __launch_bounds__(512, 2) mega_fwd(Params P) {
;     ...
;         for (int rep_ = 0; rep_ < ((PROBE_DUP & 32) ? 2 : 1); ++rep_) PH(1) { PHASE_BEGIN
;             const int tid = opaque_tid(), lane = tid & 63, wave = __builtin_amdgcn_readfirstlane(tid >> 6); const int gw = c * 8 + wave, NGW = (G + z) * 8;
;             const float* wf1 = PIN(I_WF1) + (size_t)l * D * 2 * DFF; const float* wf2 = PIN(I_WF2) + (size_t)l * DFF * D;
;             const int n1 = 32 * 44, n2 = 88 * 8;
;             { const int tot4 = (n1 + n2) * 4; const int s0 = (int)((unsigned)(gw * tot4) / (unsigned)NGW), s1 = (int)((unsigned)((gw + 1) * tot4) / (unsigned)NGW);
;             for (int ss = s0; ss < s1; ++ss) {
;                 const int it = ss >> 2, sub = ss & 3;
;                 if (it < n1) transpose_item<1>(wf1, D, 2 * DFF, WF1, it, sub, lane);
;                 else transpose_item<0>(wf2, DFF, D, WF2, it - n1, sub, lane);
;             } }
;         }
;         GSYNC();
.LBB0_1584:
	s_cmpk_eq_u32 s100, 0xd4
	s_cbranch_scc1 .Lw2_ret
	s_waitcnt vmcnt(0)
	s_barrier
	s_mov_b64 s[0:1], exec
	v_readlane_b32 s4, v252, 2
	v_readlane_b32 s5, v252, 3
	s_and_b64 s[4:5], s[0:1], s[4:5]
	s_mov_b64 exec, s[4:5]
	s_cbranch_execz .LBB0_1636
	v_readlane_b32 s4, v254, 18
	s_waitcnt vmcnt(0) expcnt(0) lgkmcnt(0)
	s_nop 0
	v_mov_b32_e32 v0, s4
	ds_read_b32 v3, v0
	v_readlane_b32 s4, v254, 19
	s_waitcnt lgkmcnt(0)
	v_cmp_ne_u32_e32 vcc, 0, v3
	v_mov_b32_e32 v0, s4
	ds_read_b32 v2, v0
	s_cbranch_vccnz .LBB0_1600
	s_mov_b32 s18, 1
	s_branch .LBB0_1588

; #define PH(b) if ((PHM >> (b)) & 1)
; #define PHASE_BEGIN unsigned char* ws = opaque_ptr(P.ws); const int z = opaque_zero(); (void)ws; (void)z;
; #define GSYNC() xcd_barrier(xbar)
; __global__ void __launch_bounds__(512, 2) mega_fwd(Params P) {
;     ...
;         PH(11) { PHASE_BEGIN
;           pg8::SplitOrder S{HID, WF2, DFF, DFF, MP / 256, 8, G, c, DFF / 64, 11, 8}; pg8::EpiMix E{FFO, D, PART, 11};
;     ...
;           pg8::gemm_phase(lds, DFF, DFF, S, E);
;     ...
;           pg8::gemm_phase(lds, DFF, DFF, S, E); }
;         GSYNC();
.LBB0_1655:
	s_waitcnt vmcnt(0)
	v_readlane_b32 s51, v254, 48
	s_movk_i32 s42, 0x40ff
	v_readlane_b32 s52, v254, 50
	s_mov_b32 s53, 0x8000
	s_mov_b32 s54, 0xa000
	s_mov_b32 s55, 0xc000
	s_mov_b32 s56, 0xe000
	s_mov_b32 s57, 0x16000
	v_readlane_b32 s24, v254, 57
	s_barrier
	v_readlane_b32 s25, v254, 58
	s_cmpk_lt_u32 s2, 0x2c
	s_cbranch_scc1 .Lg4_tail_skip
	v_writelane_b32 v255, s0, 8
	s_nop 1
	v_writelane_b32 v255, s1, 9
	s_nop 1
	v_writelane_b32 v255, s4, 10
	s_nop 1
	v_writelane_b32 v255, s5, 11
	s_nop 1
	v_writelane_b32 v255, s14, 12
	s_nop 1
	v_writelane_b32 v255, s15, 13
	s_nop 1
	v_writelane_b32 v255, s16, 14
	s_nop 1
	v_writelane_b32 v255, s17, 15
	s_nop 1
	v_writelane_b32 v255, s18, 16
	s_nop 1
	v_writelane_b32 v255, s19, 17
	s_nop 1
	v_writelane_b32 v255, s24, 18
	s_nop 1
	v_writelane_b32 v255, s25, 19
	s_nop 1
	v_writelane_b32 v255, s28, 20
	s_nop 1
	v_writelane_b32 v255, s29, 21
	s_nop 1
	v_writelane_b32 v255, s30, 22
	s_nop 1
	v_writelane_b32 v255, s31, 23
	s_nop 1
	v_writelane_b32 v255, s68, 24
	s_nop 1
	s_movk_i32 s100, 0xd4
	s_sub_u32 s101, s2, 0x2c
	s_lshl_b32 s101, s101, 3
	s_movk_i32 s4, 0xb00
	v_writelane_b32 v255, s4, 50
	s_nop 1
	s_movk_i32 s4, 0x1600
	v_writelane_b32 v255, s4, 51
	s_nop 1
	s_branch .Lw2_entry
.Lw2_ret:
	s_mov_b64 exec, -1
	s_waitcnt vmcnt(0) lgkmcnt(0)
	v_readlane_b32 s0, v255, 8
	v_readlane_b32 s1, v255, 9
	v_readlane_b32 s4, v255, 10
	v_readlane_b32 s5, v255, 11
	v_readlane_b32 s14, v255, 12
	v_readlane_b32 s15, v255, 13
	v_readlane_b32 s16, v255, 14
	v_readlane_b32 s17, v255, 15
	v_readlane_b32 s18, v255, 16
	v_readlane_b32 s19, v255, 17
	v_readlane_b32 s24, v255, 18
	v_readlane_b32 s25, v255, 19
	v_readlane_b32 s28, v255, 20
	v_readlane_b32 s29, v255, 21
	v_readlane_b32 s30, v255, 22
	v_readlane_b32 s31, v255, 23
	v_readlane_b32 s68, v255, 24
	s_nop 4
.Lg4_tail_skip:
.LBB0_1656:
	s_waitcnt vmcnt(0)
	s_waitcnt vmcnt(0)
	s_barrier
	s_mov_b64 s[0:1], exec
	v_readlane_b32 s4, v252, 2
	v_readlane_b32 s5, v252, 3
	s_and_b64 s[4:5], s[0:1], s[4:5]
	s_mov_b64 exec, s[4:5]
	s_cbranch_execz .LBB0_1708
	v_readlane_b32 s4, v254, 18
	s_waitcnt vmcnt(0) expcnt(0) lgkmcnt(0)
	s_nop 0
	v_mov_b32_e32 v0, s4
	ds_read_b32 v3, v0
	v_readlane_b32 s4, v254, 19
	s_waitcnt lgkmcnt(0)
	v_cmp_ne_u32_e32 vcc, 0, v3
	v_mov_b32_e32 v0, s4
	ds_read_b32 v2, v0
	s_cbranch_vccnz .LBB0_1672
	s_mov_b32 s18, 1
	s_branch .LBB0_1660
